# job1 pad trimming: the sixteen V fragment reads fill the MFMA-to-VALU hazard pad after each QK chain (s_nop 11 removed), duplicates removed from both softmax paths
# baseline (speedup 1.0000x reference)
.LBB0_1165:
	s_sub_i32 s45, s42, 64
	s_cmp_ge_u32 s45, s66
	s_cselect_b64 s[48:49], -1, 0
	s_cmp_gt_i32 s44, s39
	s_cselect_b64 s[50:51], -1, 0
	s_or_b64 s[48:49], s[50:51], s[48:49]
	s_and_b64 vcc, exec, s[48:49]
	s_cbranch_vccnz .LBB0_1169
	v_add_u32_e32 v120, v124, v198
	ds_read_b128 v[136:139], v120
	ds_read_b128 v[140:143], v120 offset:6656
	ds_read_b128 v[144:147], v120 offset:32
	ds_read_b128 v[148:151], v120 offset:6688
	ds_read_b128 v[152:155], v120 offset:64
	ds_read_b128 v[156:159], v120 offset:6720
	ds_read_b128 v[160:163], v120 offset:96
	ds_read_b128 v[164:167], v120 offset:6752
	ds_read_b128 v[168:171], v120 offset:128
	ds_read_b128 v[172:175], v120 offset:6784
	ds_read_b128 v[176:179], v120 offset:160
	ds_read_b128 v[180:183], v120 offset:6816
	v_add_u32_e32 v184, v125, v126
	s_waitcnt lgkmcnt(11)
	v_mfma_f32_32x32x16_bf16 v[34:49], v[136:139], v[66:69], v[220:235]
	s_waitcnt lgkmcnt(10)
	v_mfma_f32_32x32x16_bf16 v[50:65], v[140:143], v[66:69], v[220:235]
	s_waitcnt lgkmcnt(9)
	v_mfma_f32_32x32x16_bf16 v[34:49], v[144:147], v[70:73], v[34:49]
	s_waitcnt lgkmcnt(8)
	v_mfma_f32_32x32x16_bf16 v[50:65], v[148:151], v[70:73], v[50:65]
	s_waitcnt lgkmcnt(7)
	v_mfma_f32_32x32x16_bf16 v[34:49], v[152:155], v[74:77], v[34:49]
	s_waitcnt lgkmcnt(6)
	v_mfma_f32_32x32x16_bf16 v[50:65], v[156:159], v[74:77], v[50:65]
	s_waitcnt lgkmcnt(5)
	v_mfma_f32_32x32x16_bf16 v[34:49], v[160:163], v[78:81], v[34:49]
	s_waitcnt lgkmcnt(4)
	v_mfma_f32_32x32x16_bf16 v[50:65], v[164:167], v[78:81], v[50:65]
	s_waitcnt lgkmcnt(3)
	v_mfma_f32_32x32x16_bf16 v[34:49], v[168:171], v[106:109], v[34:49]
	s_waitcnt lgkmcnt(2)
	v_mfma_f32_32x32x16_bf16 v[50:65], v[172:175], v[106:109], v[50:65]
	s_waitcnt lgkmcnt(1)
	v_mfma_f32_32x32x16_bf16 v[34:49], v[176:179], v[110:113], v[34:49]
	s_waitcnt lgkmcnt(0)
	v_mfma_f32_32x32x16_bf16 v[50:65], v[180:183], v[110:113], v[50:65]
	ds_read_b64_tr_b16 v[136:137], v184 offset:13312
	ds_read_b64_tr_b16 v[138:139], v184 offset:14464
	ds_read_b64_tr_b16 v[140:141], v184 offset:13376
	ds_read_b64_tr_b16 v[142:143], v184 offset:14528
	ds_read_b64_tr_b16 v[144:145], v184 offset:15616
	ds_read_b64_tr_b16 v[146:147], v184 offset:16768
	ds_read_b64_tr_b16 v[148:149], v184 offset:15680
	ds_read_b64_tr_b16 v[150:151], v184 offset:16832
	ds_read_b64_tr_b16 v[152:153], v184 offset:17920
	ds_read_b64_tr_b16 v[154:155], v184 offset:19072
	ds_read_b64_tr_b16 v[156:157], v184 offset:17984
	ds_read_b64_tr_b16 v[158:159], v184 offset:19136
	ds_read_b64_tr_b16 v[160:161], v184 offset:20224
	ds_read_b64_tr_b16 v[162:163], v184 offset:21376
	ds_read_b64_tr_b16 v[164:165], v184 offset:20288
	ds_read_b64_tr_b16 v[166:167], v184 offset:21440
	v_max3_f32 v120, v34, v35, v36
	v_max3_f32 v130, v51, v52, v53
	v_max3_f32 v120, v120, v37, v38
	v_max3_f32 v130, v130, v54, v55
	v_max3_f32 v120, v120, v39, v40
	v_max3_f32 v130, v130, v56, v57
	v_max3_f32 v120, v120, v41, v42
	v_max3_f32 v130, v130, v58, v59
	v_max3_f32 v120, v120, v43, v44
	v_max3_f32 v130, v130, v60, v61
	v_max3_f32 v120, v120, v45, v46
	v_max3_f32 v130, v130, v62, v63
	v_max3_f32 v120, v120, v47, v48
	v_max3_f32 v130, v130, v64, v65
	v_max3_f32 v120, v120, v49, v50
	v_max_f32_e32 v120, v120, v130
	v_sub_f32_e32 v130, v236, v120
	v_cmp_gt_f32_e32 vcc, 0xc2800000, v130
	s_cbranch_vccnz .Llazy8_full
	v_mov_b32_e32 v130, v129
	v_mov_b32_e32 v120, 1.0
	s_branch .LBB0_1168
.Llazy8_full:
	v_and_b32_e32 v131, 64, v218
	v_xor_b32_e32 v130, 32, v218
	v_add_u32_e32 v131, 64, v131
	v_cmp_lt_i32_e32 vcc, v130, v131
	s_nop 1
	v_cndmask_b32_e32 v130, v218, v130, vcc
	v_lshlrev_b32_e32 v130, 2, v130
	ds_bpermute_b32 v130, v130, v120
	s_waitcnt lgkmcnt(0)
	v_max_f32_e32 v130, v120, v130
	v_max_f32_e32 v130, v130, v236
	v_max_f32_e32 v120, 0, v130
	v_exp_f32_e64 v120, -v120
	v_mov_b32_e32 v236, 0
	v_sub_f32_e32 v34, v34, v130
	v_sub_f32_e32 v35, v35, v130
	v_sub_f32_e32 v36, v36, v130
	v_sub_f32_e32 v37, v37, v130
	v_sub_f32_e32 v38, v38, v130
	v_sub_f32_e32 v39, v39, v130
	v_sub_f32_e32 v40, v40, v130
	v_sub_f32_e32 v41, v41, v130
	v_sub_f32_e32 v42, v42, v130
	v_sub_f32_e32 v43, v43, v130
	v_sub_f32_e32 v44, v44, v130
	v_sub_f32_e32 v45, v45, v130
	v_sub_f32_e32 v46, v46, v130
	v_sub_f32_e32 v47, v47, v130
	v_sub_f32_e32 v48, v48, v130
	v_sub_f32_e32 v49, v49, v130
	v_sub_f32_e32 v50, v50, v130
	v_sub_f32_e32 v51, v51, v130
	v_sub_f32_e32 v52, v52, v130
	v_sub_f32_e32 v53, v53, v130
	v_sub_f32_e32 v54, v54, v130
	v_sub_f32_e32 v55, v55, v130
	v_sub_f32_e32 v56, v56, v130
	v_sub_f32_e32 v57, v57, v130
	v_sub_f32_e32 v58, v58, v130
	v_sub_f32_e32 v59, v59, v130
	v_sub_f32_e32 v60, v60, v130
	v_sub_f32_e32 v61, v61, v130
	v_sub_f32_e32 v62, v62, v130
	v_sub_f32_e32 v63, v63, v130
	v_sub_f32_e32 v64, v64, v130
	v_sub_f32_e32 v65, v65, v130
	v_sub_f32_e32 v220, v220, v130
	v_sub_f32_e32 v221, v221, v130
	v_sub_f32_e32 v222, v222, v130
	v_sub_f32_e32 v223, v223, v130
	v_sub_f32_e32 v224, v224, v130
	v_sub_f32_e32 v225, v225, v130
	v_sub_f32_e32 v226, v226, v130
	v_sub_f32_e32 v227, v227, v130
	v_sub_f32_e32 v228, v228, v130
	v_sub_f32_e32 v229, v229, v130
	v_sub_f32_e32 v230, v230, v130
	v_sub_f32_e32 v231, v231, v130
	v_sub_f32_e32 v232, v232, v130
	v_sub_f32_e32 v233, v233, v130
	v_sub_f32_e32 v234, v234, v130
	v_sub_f32_e32 v235, v235, v130
	v_cmp_neq_f32_e32 vcc, 1.0, v120
	s_cbranch_vccz .LBB0_1168
	v_pk_mul_f32 v[16:17], v[16:17], v[120:121] op_sel_hi:[1,0]
	v_pk_mul_f32 v[14:15], v[14:15], v[120:121] op_sel_hi:[1,0]
	v_pk_mul_f32 v[12:13], v[12:13], v[120:121] op_sel_hi:[1,0]
	v_pk_mul_f32 v[10:11], v[10:11], v[120:121] op_sel_hi:[1,0]
	v_pk_mul_f32 v[8:9], v[8:9], v[120:121] op_sel_hi:[1,0]
	v_pk_mul_f32 v[6:7], v[6:7], v[120:121] op_sel_hi:[1,0]
	v_pk_mul_f32 v[4:5], v[4:5], v[120:121] op_sel_hi:[1,0]
	v_pk_mul_f32 v[2:3], v[2:3], v[120:121] op_sel_hi:[1,0]
	v_pk_mul_f32 v[32:33], v[32:33], v[120:121] op_sel_hi:[1,0]
	v_pk_mul_f32 v[30:31], v[30:31], v[120:121] op_sel_hi:[1,0]
	v_pk_mul_f32 v[28:29], v[28:29], v[120:121] op_sel_hi:[1,0]
	v_pk_mul_f32 v[26:27], v[26:27], v[120:121] op_sel_hi:[1,0]
	v_pk_mul_f32 v[24:25], v[24:25], v[120:121] op_sel_hi:[1,0]
	v_pk_mul_f32 v[22:23], v[22:23], v[120:121] op_sel_hi:[1,0]
	v_pk_mul_f32 v[20:21], v[20:21], v[120:121] op_sel_hi:[1,0]
	v_pk_mul_f32 v[18:19], v[18:19], v[120:121] op_sel_hi:[1,0]

.LBB0_1179:
	s_cmp_ge_u32 s42, s66
	s_cselect_b64 s[48:49], -1, 0
	s_cmp_ge_i32 s44, s39
	s_cselect_b64 s[50:51], -1, 0
	s_or_b64 s[48:49], s[50:51], s[48:49]
	s_and_b64 vcc, exec, s[48:49]
	s_cbranch_vccnz .LBB0_1184
	v_add_u32_e32 v120, v124, v198
	ds_read_b128 v[136:139], v120 offset:32768
	ds_read_b128 v[140:143], v120 offset:39424
	ds_read_b128 v[144:147], v120 offset:32800
	ds_read_b128 v[148:151], v120 offset:39456
	ds_read_b128 v[152:155], v120 offset:32832
	ds_read_b128 v[156:159], v120 offset:39488
	ds_read_b128 v[160:163], v120 offset:32864
	ds_read_b128 v[164:167], v120 offset:39520
	ds_read_b128 v[168:171], v120 offset:32896
	ds_read_b128 v[172:175], v120 offset:39552
	ds_read_b128 v[176:179], v120 offset:32928
	ds_read_b128 v[180:183], v120 offset:39584
	v_add_u32_e32 v184, v125, v126
	s_waitcnt lgkmcnt(11)
	v_mfma_f32_32x32x16_bf16 v[34:49], v[136:139], v[66:69], v[220:235]
	s_waitcnt lgkmcnt(10)
	v_mfma_f32_32x32x16_bf16 v[50:65], v[140:143], v[66:69], v[220:235]
	s_waitcnt lgkmcnt(9)
	v_mfma_f32_32x32x16_bf16 v[34:49], v[144:147], v[70:73], v[34:49]
	s_waitcnt lgkmcnt(8)
	v_mfma_f32_32x32x16_bf16 v[50:65], v[148:151], v[70:73], v[50:65]
	s_waitcnt lgkmcnt(7)
	v_mfma_f32_32x32x16_bf16 v[34:49], v[152:155], v[74:77], v[34:49]
	s_waitcnt lgkmcnt(6)
	v_mfma_f32_32x32x16_bf16 v[50:65], v[156:159], v[74:77], v[50:65]
	s_waitcnt lgkmcnt(5)
	v_mfma_f32_32x32x16_bf16 v[34:49], v[160:163], v[78:81], v[34:49]
	s_waitcnt lgkmcnt(4)
	v_mfma_f32_32x32x16_bf16 v[50:65], v[164:167], v[78:81], v[50:65]
	s_waitcnt lgkmcnt(3)
	v_mfma_f32_32x32x16_bf16 v[34:49], v[168:171], v[106:109], v[34:49]
	s_waitcnt lgkmcnt(2)
	v_mfma_f32_32x32x16_bf16 v[50:65], v[172:175], v[106:109], v[50:65]
	s_waitcnt lgkmcnt(1)
	v_mfma_f32_32x32x16_bf16 v[34:49], v[176:179], v[110:113], v[34:49]
	s_waitcnt lgkmcnt(0)
	v_mfma_f32_32x32x16_bf16 v[50:65], v[180:183], v[110:113], v[50:65]
	ds_read_b64_tr_b16 v[136:137], v184 offset:46080
	ds_read_b64_tr_b16 v[138:139], v184 offset:47232
	ds_read_b64_tr_b16 v[140:141], v184 offset:46144
	ds_read_b64_tr_b16 v[142:143], v184 offset:47296
	ds_read_b64_tr_b16 v[144:145], v184 offset:48384
	ds_read_b64_tr_b16 v[146:147], v184 offset:49536
	ds_read_b64_tr_b16 v[148:149], v184 offset:48448
	ds_read_b64_tr_b16 v[150:151], v184 offset:49600
	ds_read_b64_tr_b16 v[152:153], v184 offset:50688
	ds_read_b64_tr_b16 v[154:155], v184 offset:51840
	ds_read_b64_tr_b16 v[156:157], v184 offset:50752
	ds_read_b64_tr_b16 v[158:159], v184 offset:51904
	ds_read_b64_tr_b16 v[160:161], v184 offset:52992
	ds_read_b64_tr_b16 v[162:163], v184 offset:54144
	ds_read_b64_tr_b16 v[164:165], v184 offset:53056
	ds_read_b64_tr_b16 v[166:167], v184 offset:54208
	v_max3_f32 v120, v34, v35, v36
	v_max3_f32 v129, v51, v52, v53
	v_max3_f32 v120, v120, v37, v38
	v_max3_f32 v129, v129, v54, v55
	v_max3_f32 v120, v120, v39, v40
	v_max3_f32 v129, v129, v56, v57
	v_max3_f32 v120, v120, v41, v42
	v_max3_f32 v129, v129, v58, v59
	v_max3_f32 v120, v120, v43, v44
	v_max3_f32 v129, v129, v60, v61
	v_max3_f32 v120, v120, v45, v46
	v_max3_f32 v129, v129, v62, v63
	v_max3_f32 v120, v120, v47, v48
	v_max3_f32 v129, v129, v64, v65
	v_max3_f32 v120, v120, v49, v50
	v_max_f32_e32 v120, v120, v129
	v_sub_f32_e32 v129, v236, v120
	v_cmp_gt_f32_e32 vcc, 0xc2800000, v129
	s_cbranch_vccnz .Llazy9_full
	v_mov_b32_e32 v129, v130
	v_mov_b32_e32 v120, 1.0
	s_branch .LBB0_1182
.Llazy9_full:
	v_and_b32_e32 v131, 64, v218
	v_xor_b32_e32 v129, 32, v218
	v_add_u32_e32 v131, 64, v131
	v_cmp_lt_i32_e32 vcc, v129, v131
	s_nop 1
	v_cndmask_b32_e32 v129, v218, v129, vcc
	v_lshlrev_b32_e32 v129, 2, v129
	ds_bpermute_b32 v129, v129, v120
	s_waitcnt lgkmcnt(0)
	v_max_f32_e32 v129, v120, v129
	v_max_f32_e32 v129, v129, v236
	v_max_f32_e32 v120, 0, v129
	v_exp_f32_e64 v120, -v120
	v_mov_b32_e32 v236, 0
	v_sub_f32_e32 v34, v34, v129
	v_sub_f32_e32 v35, v35, v129
	v_sub_f32_e32 v36, v36, v129
	v_sub_f32_e32 v37, v37, v129
	v_sub_f32_e32 v38, v38, v129
	v_sub_f32_e32 v39, v39, v129
	v_sub_f32_e32 v40, v40, v129
	v_sub_f32_e32 v41, v41, v129
	v_sub_f32_e32 v42, v42, v129
	v_sub_f32_e32 v43, v43, v129
	v_sub_f32_e32 v44, v44, v129
	v_sub_f32_e32 v45, v45, v129
	v_sub_f32_e32 v46, v46, v129
	v_sub_f32_e32 v47, v47, v129
	v_sub_f32_e32 v48, v48, v129
	v_sub_f32_e32 v49, v49, v129
	v_sub_f32_e32 v50, v50, v129
	v_sub_f32_e32 v51, v51, v129
	v_sub_f32_e32 v52, v52, v129
	v_sub_f32_e32 v53, v53, v129
	v_sub_f32_e32 v54, v54, v129
	v_sub_f32_e32 v55, v55, v129
	v_sub_f32_e32 v56, v56, v129
	v_sub_f32_e32 v57, v57, v129
	v_sub_f32_e32 v58, v58, v129
	v_sub_f32_e32 v59, v59, v129
	v_sub_f32_e32 v60, v60, v129
	v_sub_f32_e32 v61, v61, v129
	v_sub_f32_e32 v62, v62, v129
	v_sub_f32_e32 v63, v63, v129
	v_sub_f32_e32 v64, v64, v129
	v_sub_f32_e32 v65, v65, v129
	v_sub_f32_e32 v220, v220, v129
	v_sub_f32_e32 v221, v221, v129
	v_sub_f32_e32 v222, v222, v129
	v_sub_f32_e32 v223, v223, v129
	v_sub_f32_e32 v224, v224, v129
	v_sub_f32_e32 v225, v225, v129
	v_sub_f32_e32 v226, v226, v129
	v_sub_f32_e32 v227, v227, v129
	v_sub_f32_e32 v228, v228, v129
	v_sub_f32_e32 v229, v229, v129
	v_sub_f32_e32 v230, v230, v129
	v_sub_f32_e32 v231, v231, v129
	v_sub_f32_e32 v232, v232, v129
	v_sub_f32_e32 v233, v233, v129
	v_sub_f32_e32 v234, v234, v129
	v_sub_f32_e32 v235, v235, v129
	v_cmp_neq_f32_e32 vcc, 1.0, v120
	s_cbranch_vccz .LBB0_1182
	v_pk_mul_f32 v[16:17], v[16:17], v[120:121] op_sel_hi:[1,0]
	v_pk_mul_f32 v[14:15], v[14:15], v[120:121] op_sel_hi:[1,0]
	v_pk_mul_f32 v[12:13], v[12:13], v[120:121] op_sel_hi:[1,0]
	v_pk_mul_f32 v[10:11], v[10:11], v[120:121] op_sel_hi:[1,0]
	v_pk_mul_f32 v[8:9], v[8:9], v[120:121] op_sel_hi:[1,0]
	v_pk_mul_f32 v[6:7], v[6:7], v[120:121] op_sel_hi:[1,0]
	v_pk_mul_f32 v[4:5], v[4:5], v[120:121] op_sel_hi:[1,0]
	v_pk_mul_f32 v[2:3], v[2:3], v[120:121] op_sel_hi:[1,0]
	v_pk_mul_f32 v[32:33], v[32:33], v[120:121] op_sel_hi:[1,0]
	v_pk_mul_f32 v[30:31], v[30:31], v[120:121] op_sel_hi:[1,0]
	v_pk_mul_f32 v[28:29], v[28:29], v[120:121] op_sel_hi:[1,0]
	v_pk_mul_f32 v[26:27], v[26:27], v[120:121] op_sel_hi:[1,0]
	v_pk_mul_f32 v[24:25], v[24:25], v[120:121] op_sel_hi:[1,0]
	v_pk_mul_f32 v[22:23], v[22:23], v[120:121] op_sel_hi:[1,0]
	v_pk_mul_f32 v[20:21], v[20:21], v[120:121] op_sel_hi:[1,0]
	v_pk_mul_f32 v[18:19], v[18:19], v[120:121] op_sel_hi:[1,0]
